# pool-GEMM epilogue: bias and scale vectors loaded once per tile (16 loads in flight) instead of 32 serialized load pairs
# speedup vs baseline: 1.0653x; 1.0021x over previous
.LBB0_2118:
	s_ashr_i32 s2, s87, 31
	s_lshr_b32 s2, s2, 30
	s_add_i32 s2, s87, s2
	s_ashr_i32 s18, s2, 2
	s_and_b32 s2, s2, -4
	s_sub_i32 s2, s87, s2
	s_ashr_i32 s3, s2, 31
	s_lshl_b64 s[2:3], s[2:3], 17
	s_add_u32 s2, s25, s2
	s_addc_u32 s3, s26, s3
	s_ashr_i32 s19, s18, 31
	s_lshl_b64 s[4:5], s[18:19], 19
	s_add_u32 s19, s27, s4
	s_addc_u32 s5, s28, s5
	s_lshl_b32 s4, s18, 10
	s_sub_i32 s20, s31, s4
	s_ashr_i32 s21, s20, 31
	s_lshl_b64 s[6:7], s[20:21], 1
	v_mov_b32_e32 v16, v184
	s_add_u32 s6, s19, s6
	s_addc_u32 s7, s5, s7
	v_ashrrev_i32_e32 v17, 6, v16
	v_bfe_u32 v10, v16, 3, 3
	v_bitop3_b32 v0, v10, v16, 7 bitop3:0x78
	v_readfirstlane_b32 s5, v17
	v_lshlrev_b32_e32 v12, 4, v0
	s_lshl_b32 s19, s5, 2
	v_lshl_or_b32 v0, s5, 5, v10
	s_lshl_b32 s97, s5, 12
	s_waitcnt lgkmcnt(0)
	s_barrier
	v_lshl_or_b32 v134, v0, 9, v12
	s_mov_b32 m0, s97
	s_add_i32 s90, s97, 0x8000
	s_or_b32 s5, s19, 1
	v_lshl_add_u64 v[14:15], s[2:3], 0, v[134:135]
	global_load_lds_dwordx4 v134, s[2:3]
	v_lshl_or_b32 v134, v0, 11, v12
	s_mov_b32 m0, s90
	v_lshl_or_b32 v4, s5, 3, v10
	s_lshl_b32 s91, s5, 10
	v_lshl_add_u64 v[0:1], s[6:7], 0, v[134:135]
	global_load_lds_dwordx4 v134, s[6:7]
	v_lshl_or_b32 v134, v4, 9, v12
	s_mov_b32 m0, s91
	s_add_i32 s92, s91, 0x8000
	s_or_b32 s5, s19, 2
	v_lshl_add_u64 v[2:3], s[2:3], 0, v[134:135]
	global_load_lds_dwordx4 v134, s[2:3]
	v_lshl_or_b32 v134, v4, 11, v12
	s_mov_b32 m0, s92
	v_lshl_or_b32 v8, s5, 3, v10
	s_lshl_b32 s93, s5, 10
	v_lshl_add_u64 v[4:5], s[6:7], 0, v[134:135]
	global_load_lds_dwordx4 v134, s[6:7]
	v_lshl_or_b32 v134, v8, 9, v12
	s_mov_b32 m0, s93
	s_add_i32 s94, s93, 0x8000
	s_or_b32 s5, s19, 3
	v_lshl_add_u64 v[6:7], s[2:3], 0, v[134:135]
	global_load_lds_dwordx4 v134, s[2:3]
	v_lshl_or_b32 v134, v8, 11, v12
	s_mov_b32 m0, s94
	v_lshl_or_b32 v13, s5, 3, v10
	s_lshl_b32 s95, s5, 10
	v_bfe_u32 v19, v16, 4, 2
	v_lshl_add_u64 v[8:9], s[6:7], 0, v[134:135]
	global_load_lds_dwordx4 v134, s[6:7]
	v_lshl_or_b32 v134, v13, 9, v12
	s_mov_b32 m0, s95
	s_add_i32 s96, s95, 0x8000
	v_bitop3_b32 v20, v19, v16, 7 bitop3:0x78
	v_lshl_add_u64 v[10:11], s[2:3], 0, v[134:135]
	global_load_lds_dwordx4 v134, s[2:3]
	v_lshl_or_b32 v134, v13, 11, v12
	s_mov_b32 m0, s96
	v_lshlrev_b32_e32 v36, 4, v20
	v_lshlrev_b32_e32 v20, 7, v16
	v_and_b32_e32 v18, 7, v16
	global_load_lds_dwordx4 v134, s[6:7]
	v_and_b32_e32 v20, 0x780, v20
	v_lshlrev_b32_e32 v16, 6, v16
	v_lshl_add_u64 v[12:13], s[6:7], 0, v[134:135]
	s_waitcnt vmcnt(0)
	v_lshlrev_b32_e32 v17, 13, v17
	v_and_or_b32 v134, v16, s85, v20
	v_bitop3_b32 v16, v19, v18, 4 bitop3:0x36
	s_add_i32 s23, s97, 0x10000
	s_waitcnt lgkmcnt(0)
	s_barrier
	v_and_or_b32 v116, v17, s83, v20
	v_lshlrev_b32_e32 v136, 4, v16
	v_lshl_add_u64 v[16:17], v[14:15], 0, s[52:53]
	s_mov_b32 m0, s23
	s_add_i32 s22, s97, 0x18000
	global_load_lds_dwordx4 v[16:17], off
	v_lshl_add_u64 v[16:17], v[0:1], 0, s[52:53]
	s_mov_b32 m0, s22
	s_add_i32 s19, s91, 0x10000
	global_load_lds_dwordx4 v[16:17], off
	v_lshl_add_u64 v[16:17], v[2:3], 0, s[52:53]
	s_mov_b32 m0, s19
	s_add_i32 s7, s91, 0x18000
	global_load_lds_dwordx4 v[16:17], off
	v_lshl_add_u64 v[16:17], v[4:5], 0, s[52:53]
	s_mov_b32 m0, s7
	s_add_i32 s6, s93, 0x10000
	global_load_lds_dwordx4 v[16:17], off
	v_lshl_add_u64 v[16:17], v[6:7], 0, s[52:53]
	s_mov_b32 m0, s6
	s_add_i32 s5, s93, 0x18000
	global_load_lds_dwordx4 v[16:17], off
	v_lshl_add_u64 v[16:17], v[8:9], 0, s[52:53]
	s_mov_b32 m0, s5
	s_add_i32 s3, s95, 0x10000
	global_load_lds_dwordx4 v[16:17], off
	v_lshl_add_u64 v[16:17], v[10:11], 0, s[52:53]
	s_mov_b32 m0, s3
	s_add_i32 s2, s95, 0x18000
	global_load_lds_dwordx4 v[16:17], off
	v_lshl_add_u64 v[16:17], v[12:13], 0, s[52:53]
	s_mov_b32 m0, s2
	v_or_b32_e32 v18, v36, v116
	global_load_lds_dwordx4 v[16:17], off
	v_or_b32_e32 v17, v36, v134
	ds_read_b128 v[20:23], v18 offset:32768
	ds_read_b128 v[24:27], v18 offset:34816
	ds_read_b128 v[28:31], v18 offset:36864
	ds_read_b128 v[32:35], v18 offset:38912
	ds_read_b128 v[36:39], v17
	ds_read_b128 v[40:43], v17 offset:2048
	ds_read_b128 v[44:47], v17 offset:4096
	ds_read_b128 v[48:51], v17 offset:6144
	ds_read_b128 v[52:55], v17 offset:8192
	ds_read_b128 v[56:59], v17 offset:10240
	ds_read_b128 v[60:63], v17 offset:12288
	ds_read_b128 v[64:67], v17 offset:14336
	s_waitcnt lgkmcnt(0)
	v_mfma_f32_16x16x32_bf16 v[68:71], v[36:39], v[20:23], 0
	v_mfma_f32_16x16x32_bf16 v[72:75], v[36:39], v[24:27], 0
	v_mfma_f32_16x16x32_bf16 v[76:79], v[36:39], v[28:31], 0
	v_mfma_f32_16x16x32_bf16 v[36:39], v[36:39], v[32:35], 0
	v_mfma_f32_16x16x32_bf16 v[80:83], v[40:43], v[20:23], 0
	v_mfma_f32_16x16x32_bf16 v[84:87], v[40:43], v[24:27], 0
	v_mfma_f32_16x16x32_bf16 v[88:91], v[40:43], v[28:31], 0
	v_mfma_f32_16x16x32_bf16 v[40:43], v[40:43], v[32:35], 0
	v_mfma_f32_16x16x32_bf16 v[92:95], v[44:47], v[20:23], 0
	v_mfma_f32_16x16x32_bf16 v[96:99], v[44:47], v[24:27], 0
	v_mfma_f32_16x16x32_bf16 v[100:103], v[44:47], v[28:31], 0
	v_mfma_f32_16x16x32_bf16 v[44:47], v[44:47], v[32:35], 0
	v_mfma_f32_16x16x32_bf16 v[104:107], v[48:51], v[20:23], 0
	v_mfma_f32_16x16x32_bf16 v[108:111], v[48:51], v[24:27], 0
	v_mfma_f32_16x16x32_bf16 v[112:115], v[48:51], v[28:31], 0
	v_mfma_f32_16x16x32_bf16 v[48:51], v[48:51], v[32:35], 0
	v_or_b32_e32 v19, v136, v116
	v_or_b32_e32 v16, v136, v134
	ds_read_b128 v[116:119], v19 offset:32768
	ds_read_b128 v[120:123], v19 offset:34816
	ds_read_b128 v[124:127], v19 offset:36864
	ds_read_b128 v[128:131], v19 offset:38912
	ds_read_b128 v[136:139], v16
	ds_read_b128 v[140:143], v16 offset:2048
	ds_read_b128 v[144:147], v16 offset:4096
	ds_read_b128 v[148:151], v16 offset:6144
	v_mfma_f32_16x16x32_bf16 v[152:155], v[52:55], v[20:23], 0
	v_mfma_f32_16x16x32_bf16 v[156:159], v[52:55], v[24:27], 0
	v_mfma_f32_16x16x32_bf16 v[160:163], v[52:55], v[28:31], 0
	v_mfma_f32_16x16x32_bf16 v[52:55], v[52:55], v[32:35], 0
	v_mfma_f32_16x16x32_bf16 v[164:167], v[56:59], v[20:23], 0
	v_mfma_f32_16x16x32_bf16 v[168:171], v[56:59], v[24:27], 0
	v_mfma_f32_16x16x32_bf16 v[172:175], v[56:59], v[28:31], 0
	v_mfma_f32_16x16x32_bf16 v[56:59], v[56:59], v[32:35], 0
	v_mfma_f32_16x16x32_bf16 v[176:179], v[60:63], v[20:23], 0
	v_mfma_f32_16x16x32_bf16 v[180:183], v[60:63], v[24:27], 0
	v_mfma_f32_16x16x32_bf16 v[198:201], v[60:63], v[28:31], 0
	v_mfma_f32_16x16x32_bf16 v[60:63], v[60:63], v[32:35], 0
	v_mfma_f32_16x16x32_bf16 v[20:23], v[64:67], v[20:23], 0
	v_mfma_f32_16x16x32_bf16 v[24:27], v[64:67], v[24:27], 0
	v_mfma_f32_16x16x32_bf16 v[28:31], v[64:67], v[28:31], 0
	v_mfma_f32_16x16x32_bf16 v[32:35], v[64:67], v[32:35], 0
	ds_read_b128 v[64:67], v16 offset:8192
	ds_read_b128 v[202:205], v16 offset:10240
	ds_read_b128 v[206:209], v16 offset:12288
	ds_read_b128 v[210:213], v16 offset:14336
	s_waitcnt lgkmcnt(0)
	v_mfma_f32_16x16x32_bf16 v[68:71], v[136:139], v[116:119], v[68:71]
	v_mfma_f32_16x16x32_bf16 v[72:75], v[136:139], v[120:123], v[72:75]
	v_mfma_f32_16x16x32_bf16 v[76:79], v[136:139], v[124:127], v[76:79]
	v_mfma_f32_16x16x32_bf16 v[36:39], v[136:139], v[128:131], v[36:39]
	v_mfma_f32_16x16x32_bf16 v[80:83], v[140:143], v[116:119], v[80:83]
	v_mfma_f32_16x16x32_bf16 v[84:87], v[140:143], v[120:123], v[84:87]
	v_mfma_f32_16x16x32_bf16 v[88:91], v[140:143], v[124:127], v[88:91]
	v_mfma_f32_16x16x32_bf16 v[40:43], v[140:143], v[128:131], v[40:43]
	v_mfma_f32_16x16x32_bf16 v[92:95], v[144:147], v[116:119], v[92:95]
	v_mfma_f32_16x16x32_bf16 v[96:99], v[144:147], v[120:123], v[96:99]
	v_mfma_f32_16x16x32_bf16 v[100:103], v[144:147], v[124:127], v[100:103]
	v_mfma_f32_16x16x32_bf16 v[44:47], v[144:147], v[128:131], v[44:47]
	v_mfma_f32_16x16x32_bf16 v[104:107], v[148:151], v[116:119], v[104:107]
	v_mfma_f32_16x16x32_bf16 v[108:111], v[148:151], v[120:123], v[108:111]
	v_mfma_f32_16x16x32_bf16 v[112:115], v[148:151], v[124:127], v[112:115]
	v_mfma_f32_16x16x32_bf16 v[48:51], v[148:151], v[128:131], v[48:51]
	s_waitcnt vmcnt(0)
	v_mfma_f32_16x16x32_bf16 v[136:139], v[64:67], v[116:119], v[152:155]
	s_waitcnt lgkmcnt(0)
	s_barrier
	v_mfma_f32_16x16x32_bf16 v[140:143], v[64:67], v[120:123], v[156:159]
	s_mov_b32 m0, s97
	v_or_b32_e32 v134, 0x18000, v18
	v_or_b32_e32 v197, 0x18800, v18
	v_mfma_f32_16x16x32_bf16 v[144:147], v[64:67], v[124:127], v[160:163]
	v_or_b32_e32 v230, 0x19000, v18
	v_or_b32_e32 v231, 0x19800, v18
	v_add_u32_e32 v232, 0x10000, v17
	v_mfma_f32_16x16x32_bf16 v[52:55], v[64:67], v[128:131], v[52:55]
	v_mfma_f32_16x16x32_bf16 v[64:67], v[202:205], v[116:119], v[164:167]
	v_mfma_f32_16x16x32_bf16 v[156:159], v[206:209], v[116:119], v[176:179]
	v_mfma_f32_16x16x32_bf16 v[20:23], v[210:213], v[116:119], v[20:23]
	v_lshl_add_u64 v[116:117], v[14:15], 0, s[54:55]
	global_load_lds_dwordx4 v[116:117], off
	v_lshl_add_u64 v[116:117], v[0:1], 0, s[54:55]
	s_mov_b32 m0, s90
	v_mfma_f32_16x16x32_bf16 v[148:151], v[202:205], v[120:123], v[168:171]
	global_load_lds_dwordx4 v[116:117], off
	v_lshl_add_u64 v[116:117], v[2:3], 0, s[54:55]
	s_mov_b32 m0, s91
	v_mfma_f32_16x16x32_bf16 v[152:155], v[202:205], v[124:127], v[172:175]
	global_load_lds_dwordx4 v[116:117], off
	v_lshl_add_u64 v[116:117], v[4:5], 0, s[54:55]
	s_mov_b32 m0, s92
	v_mfma_f32_16x16x32_bf16 v[56:59], v[202:205], v[128:131], v[56:59]
	global_load_lds_dwordx4 v[116:117], off
	v_lshl_add_u64 v[116:117], v[6:7], 0, s[54:55]
	s_mov_b32 m0, s93
	v_mfma_f32_16x16x32_bf16 v[160:163], v[206:209], v[120:123], v[180:183]
	global_load_lds_dwordx4 v[116:117], off
	v_lshl_add_u64 v[116:117], v[8:9], 0, s[54:55]
	s_mov_b32 m0, s94
	v_mfma_f32_16x16x32_bf16 v[164:167], v[206:209], v[124:127], v[198:201]
	global_load_lds_dwordx4 v[116:117], off
	v_lshl_add_u64 v[116:117], v[10:11], 0, s[54:55]
	s_mov_b32 m0, s95
	v_mfma_f32_16x16x32_bf16 v[60:63], v[206:209], v[128:131], v[60:63]
	global_load_lds_dwordx4 v[116:117], off
	v_lshl_add_u64 v[116:117], v[12:13], 0, s[54:55]
	s_mov_b32 m0, s96
	v_mfma_f32_16x16x32_bf16 v[24:27], v[210:213], v[120:123], v[24:27]
	global_load_lds_dwordx4 v[116:117], off
	ds_read_b128 v[116:119], v134
	ds_read_b128 v[120:123], v197
	v_mfma_f32_16x16x32_bf16 v[28:31], v[210:213], v[124:127], v[28:31]
	ds_read_b128 v[124:127], v230
	v_mfma_f32_16x16x32_bf16 v[32:35], v[210:213], v[128:131], v[32:35]
	ds_read_b128 v[128:131], v231
	ds_read_b128 v[168:171], v232
	ds_read_b128 v[172:175], v232 offset:2048
	ds_read_b128 v[176:179], v232 offset:4096
	ds_read_b128 v[180:183], v232 offset:6144
	ds_read_b128 v[198:201], v232 offset:8192
	ds_read_b128 v[202:205], v232 offset:10240
	ds_read_b128 v[206:209], v232 offset:12288
	ds_read_b128 v[210:213], v232 offset:14336
	s_waitcnt lgkmcnt(0)
	v_mfma_f32_16x16x32_bf16 v[68:71], v[168:171], v[116:119], v[68:71]
	v_mfma_f32_16x16x32_bf16 v[72:75], v[168:171], v[120:123], v[72:75]
	v_mfma_f32_16x16x32_bf16 v[76:79], v[168:171], v[124:127], v[76:79]
	v_mfma_f32_16x16x32_bf16 v[36:39], v[168:171], v[128:131], v[36:39]
	v_mfma_f32_16x16x32_bf16 v[80:83], v[172:175], v[116:119], v[80:83]
	v_mfma_f32_16x16x32_bf16 v[84:87], v[172:175], v[120:123], v[84:87]
	v_mfma_f32_16x16x32_bf16 v[88:91], v[172:175], v[124:127], v[88:91]
	v_mfma_f32_16x16x32_bf16 v[40:43], v[172:175], v[128:131], v[40:43]
	v_mfma_f32_16x16x32_bf16 v[92:95], v[176:179], v[116:119], v[92:95]
	v_mfma_f32_16x16x32_bf16 v[96:99], v[176:179], v[120:123], v[96:99]
	v_mfma_f32_16x16x32_bf16 v[100:103], v[176:179], v[124:127], v[100:103]
	v_mfma_f32_16x16x32_bf16 v[44:47], v[176:179], v[128:131], v[44:47]
	v_mfma_f32_16x16x32_bf16 v[104:107], v[180:183], v[116:119], v[104:107]
	v_mfma_f32_16x16x32_bf16 v[108:111], v[180:183], v[120:123], v[108:111]
	v_mfma_f32_16x16x32_bf16 v[112:115], v[180:183], v[124:127], v[112:115]
	v_mfma_f32_16x16x32_bf16 v[48:51], v[180:183], v[128:131], v[48:51]
	v_or_b32_e32 v233, 0x18000, v19
	v_or_b32_e32 v235, 0x19000, v19
	v_add_u32_e32 v238, 0x10000, v16
	v_or_b32_e32 v234, 0x18800, v19
	ds_read_b128 v[168:171], v233
	ds_read_b128 v[172:175], v234
	v_or_b32_e32 v236, 0x19800, v19
	ds_read_b128 v[176:179], v235
	ds_read_b128 v[180:183], v236
	ds_read_b128 v[214:217], v238
	ds_read_b128 v[218:221], v238 offset:2048
	ds_read_b128 v[222:225], v238 offset:4096
	ds_read_b128 v[226:229], v238 offset:6144
	v_mfma_f32_16x16x32_bf16 v[136:139], v[198:201], v[116:119], v[136:139]
	v_mfma_f32_16x16x32_bf16 v[140:143], v[198:201], v[120:123], v[140:143]
	v_mfma_f32_16x16x32_bf16 v[52:55], v[198:201], v[128:131], v[52:55]
	v_mfma_f32_16x16x32_bf16 v[64:67], v[202:205], v[116:119], v[64:67]
	v_mfma_f32_16x16x32_bf16 v[56:59], v[202:205], v[128:131], v[56:59]
	v_mfma_f32_16x16x32_bf16 v[156:159], v[206:209], v[116:119], v[156:159]
	v_mfma_f32_16x16x32_bf16 v[60:63], v[206:209], v[128:131], v[60:63]
	v_mfma_f32_16x16x32_bf16 v[20:23], v[210:213], v[116:119], v[20:23]
	v_mfma_f32_16x16x32_bf16 v[24:27], v[210:213], v[120:123], v[24:27]
	v_mfma_f32_16x16x32_bf16 v[28:31], v[210:213], v[124:127], v[28:31]
	v_mfma_f32_16x16x32_bf16 v[32:35], v[210:213], v[128:131], v[32:35]
	v_mfma_f32_16x16x32_bf16 v[144:147], v[198:201], v[124:127], v[144:147]
	v_mfma_f32_16x16x32_bf16 v[148:151], v[202:205], v[120:123], v[148:151]
	v_mfma_f32_16x16x32_bf16 v[152:155], v[202:205], v[124:127], v[152:155]
	v_mfma_f32_16x16x32_bf16 v[160:163], v[206:209], v[120:123], v[160:163]
	v_mfma_f32_16x16x32_bf16 v[164:167], v[206:209], v[124:127], v[164:167]
	ds_read_b128 v[116:119], v238 offset:8192
	ds_read_b128 v[120:123], v238 offset:10240
	ds_read_b128 v[124:127], v238 offset:12288
	ds_read_b128 v[128:131], v238 offset:14336
	s_waitcnt lgkmcnt(0)
	v_mfma_f32_16x16x32_bf16 v[68:71], v[214:217], v[168:171], v[68:71]
	v_mfma_f32_16x16x32_bf16 v[72:75], v[214:217], v[172:175], v[72:75]
	v_mfma_f32_16x16x32_bf16 v[76:79], v[214:217], v[176:179], v[76:79]
	v_mfma_f32_16x16x32_bf16 v[36:39], v[214:217], v[180:183], v[36:39]
	v_mfma_f32_16x16x32_bf16 v[80:83], v[218:221], v[168:171], v[80:83]
	v_mfma_f32_16x16x32_bf16 v[84:87], v[218:221], v[172:175], v[84:87]
	v_mfma_f32_16x16x32_bf16 v[88:91], v[218:221], v[176:179], v[88:91]
	v_mfma_f32_16x16x32_bf16 v[40:43], v[218:221], v[180:183], v[40:43]
	v_mfma_f32_16x16x32_bf16 v[92:95], v[222:225], v[168:171], v[92:95]
	v_mfma_f32_16x16x32_bf16 v[96:99], v[222:225], v[172:175], v[96:99]
	v_mfma_f32_16x16x32_bf16 v[100:103], v[222:225], v[176:179], v[100:103]
	v_mfma_f32_16x16x32_bf16 v[44:47], v[222:225], v[180:183], v[44:47]
	v_mfma_f32_16x16x32_bf16 v[104:107], v[226:229], v[168:171], v[104:107]
	v_mfma_f32_16x16x32_bf16 v[108:111], v[226:229], v[172:175], v[108:111]
	v_mfma_f32_16x16x32_bf16 v[112:115], v[226:229], v[176:179], v[112:115]
	v_mfma_f32_16x16x32_bf16 v[48:51], v[226:229], v[180:183], v[48:51]
	s_waitcnt vmcnt(0)
	s_waitcnt lgkmcnt(0)
	s_barrier
	v_lshl_add_u64 v[14:15], v[14:15], 0, s[56:57]
	s_mov_b32 m0, s23
	v_lshl_add_u64 v[0:1], v[0:1], 0, s[56:57]
	global_load_lds_dwordx4 v[14:15], off
	s_mov_b32 m0, s22
	v_mfma_f32_16x16x32_bf16 v[136:139], v[116:119], v[168:171], v[136:139]
	global_load_lds_dwordx4 v[0:1], off
	v_lshl_add_u64 v[0:1], v[2:3], 0, s[56:57]
	s_mov_b32 m0, s19
	v_mfma_f32_16x16x32_bf16 v[140:143], v[116:119], v[172:175], v[140:143]
	global_load_lds_dwordx4 v[0:1], off
	v_lshl_add_u64 v[0:1], v[4:5], 0, s[56:57]
	s_mov_b32 m0, s7
	v_mfma_f32_16x16x32_bf16 v[144:147], v[116:119], v[176:179], v[144:147]
	global_load_lds_dwordx4 v[0:1], off
	v_lshl_add_u64 v[0:1], v[6:7], 0, s[56:57]
	s_mov_b32 m0, s6
	v_mfma_f32_16x16x32_bf16 v[52:55], v[116:119], v[180:183], v[52:55]
	global_load_lds_dwordx4 v[0:1], off
	v_lshl_add_u64 v[0:1], v[8:9], 0, s[56:57]
	s_mov_b32 m0, s5
	v_mfma_f32_16x16x32_bf16 v[64:67], v[120:123], v[168:171], v[64:67]
	global_load_lds_dwordx4 v[0:1], off
	v_lshl_add_u64 v[0:1], v[10:11], 0, s[56:57]
	s_mov_b32 m0, s3
	v_mfma_f32_16x16x32_bf16 v[116:119], v[120:123], v[172:175], v[148:151]
	global_load_lds_dwordx4 v[0:1], off
	v_lshl_add_u64 v[0:1], v[12:13], 0, s[56:57]
	s_mov_b32 m0, s2
	v_mfma_f32_16x16x32_bf16 v[148:151], v[120:123], v[176:179], v[152:155]
	global_load_lds_dwordx4 v[0:1], off
	v_mfma_f32_16x16x32_bf16 v[56:59], v[120:123], v[180:183], v[56:59]
	v_mfma_f32_16x16x32_bf16 v[120:123], v[124:127], v[168:171], v[156:159]
	v_mfma_f32_16x16x32_bf16 v[152:155], v[124:127], v[172:175], v[160:163]
	v_mfma_f32_16x16x32_bf16 v[156:159], v[124:127], v[176:179], v[164:167]
	v_mfma_f32_16x16x32_bf16 v[60:63], v[124:127], v[180:183], v[60:63]
	v_mfma_f32_16x16x32_bf16 v[20:23], v[128:131], v[168:171], v[20:23]
	v_mfma_f32_16x16x32_bf16 v[24:27], v[128:131], v[172:175], v[24:27]
	v_mfma_f32_16x16x32_bf16 v[28:31], v[128:131], v[176:179], v[28:31]
	v_mfma_f32_16x16x32_bf16 v[32:35], v[128:131], v[180:183], v[32:35]
	ds_read_b128 v[0:3], v18 offset:32768
	ds_read_b128 v[4:7], v18 offset:34816
	ds_read_b128 v[8:11], v18 offset:36864
	ds_read_b128 v[12:15], v18 offset:38912
	ds_read_b128 v[124:127], v17
	ds_read_b128 v[128:131], v17 offset:2048
	ds_read_b128 v[160:163], v17 offset:4096
	ds_read_b128 v[164:167], v17 offset:6144
	ds_read_b128 v[168:171], v17 offset:8192
	ds_read_b128 v[172:175], v17 offset:10240
	ds_read_b128 v[176:179], v17 offset:12288
	ds_read_b128 v[180:183], v17 offset:14336
	s_waitcnt lgkmcnt(0)
	v_mfma_f32_16x16x32_bf16 v[68:71], v[124:127], v[0:3], v[68:71]
	v_mfma_f32_16x16x32_bf16 v[72:75], v[124:127], v[4:7], v[72:75]
	v_mfma_f32_16x16x32_bf16 v[76:79], v[124:127], v[8:11], v[76:79]
	v_mfma_f32_16x16x32_bf16 v[36:39], v[124:127], v[12:15], v[36:39]
	v_mfma_f32_16x16x32_bf16 v[80:83], v[128:131], v[0:3], v[80:83]
	v_mfma_f32_16x16x32_bf16 v[84:87], v[128:131], v[4:7], v[84:87]
	v_mfma_f32_16x16x32_bf16 v[88:91], v[128:131], v[8:11], v[88:91]
	v_mfma_f32_16x16x32_bf16 v[40:43], v[128:131], v[12:15], v[40:43]
	v_mfma_f32_16x16x32_bf16 v[92:95], v[160:163], v[0:3], v[92:95]
	v_mfma_f32_16x16x32_bf16 v[96:99], v[160:163], v[4:7], v[96:99]
	v_mfma_f32_16x16x32_bf16 v[100:103], v[160:163], v[8:11], v[100:103]
	v_mfma_f32_16x16x32_bf16 v[44:47], v[160:163], v[12:15], v[44:47]
	v_mfma_f32_16x16x32_bf16 v[104:107], v[164:167], v[0:3], v[104:107]
	v_mfma_f32_16x16x32_bf16 v[108:111], v[164:167], v[4:7], v[108:111]
	v_mfma_f32_16x16x32_bf16 v[112:115], v[164:167], v[8:11], v[112:115]
	v_mfma_f32_16x16x32_bf16 v[48:51], v[164:167], v[12:15], v[48:51]
	ds_read_b128 v[124:127], v19 offset:32768
	ds_read_b128 v[128:131], v19 offset:34816
	ds_read_b128 v[160:163], v19 offset:36864
	ds_read_b128 v[164:167], v19 offset:38912
	ds_read_b128 v[198:201], v16
	ds_read_b128 v[202:205], v16 offset:2048
	ds_read_b128 v[206:209], v16 offset:4096
	ds_read_b128 v[210:213], v16 offset:6144
	v_mfma_f32_16x16x32_bf16 v[136:139], v[168:171], v[0:3], v[136:139]
	v_mfma_f32_16x16x32_bf16 v[140:143], v[168:171], v[4:7], v[140:143]
	v_mfma_f32_16x16x32_bf16 v[144:147], v[168:171], v[8:11], v[144:147]
	v_mfma_f32_16x16x32_bf16 v[52:55], v[168:171], v[12:15], v[52:55]
	v_mfma_f32_16x16x32_bf16 v[64:67], v[172:175], v[0:3], v[64:67]
	v_mfma_f32_16x16x32_bf16 v[116:119], v[172:175], v[4:7], v[116:119]
	v_mfma_f32_16x16x32_bf16 v[148:151], v[172:175], v[8:11], v[148:151]
	v_mfma_f32_16x16x32_bf16 v[56:59], v[172:175], v[12:15], v[56:59]
	v_mfma_f32_16x16x32_bf16 v[120:123], v[176:179], v[0:3], v[120:123]
	v_mfma_f32_16x16x32_bf16 v[152:155], v[176:179], v[4:7], v[152:155]
	v_mfma_f32_16x16x32_bf16 v[156:159], v[176:179], v[8:11], v[156:159]
	v_mfma_f32_16x16x32_bf16 v[60:63], v[176:179], v[12:15], v[60:63]
	v_mfma_f32_16x16x32_bf16 v[0:3], v[180:183], v[0:3], v[20:23]
	v_mfma_f32_16x16x32_bf16 v[4:7], v[180:183], v[4:7], v[24:27]
	v_mfma_f32_16x16x32_bf16 v[8:11], v[180:183], v[8:11], v[28:31]
	v_mfma_f32_16x16x32_bf16 v[12:15], v[180:183], v[12:15], v[32:35]
	ds_read_b128 v[18:21], v16 offset:8192
	ds_read_b128 v[22:25], v16 offset:10240
	ds_read_b128 v[26:29], v16 offset:12288
	ds_read_b128 v[30:33], v16 offset:14336
	s_waitcnt lgkmcnt(0)
	v_mfma_f32_16x16x32_bf16 v[68:71], v[198:201], v[124:127], v[68:71]
	v_mfma_f32_16x16x32_bf16 v[72:75], v[198:201], v[128:131], v[72:75]
	v_mfma_f32_16x16x32_bf16 v[76:79], v[198:201], v[160:163], v[76:79]
	v_mfma_f32_16x16x32_bf16 v[34:37], v[198:201], v[164:167], v[36:39]
	v_mfma_f32_16x16x32_bf16 v[80:83], v[202:205], v[124:127], v[80:83]
	v_mfma_f32_16x16x32_bf16 v[84:87], v[202:205], v[128:131], v[84:87]
	v_mfma_f32_16x16x32_bf16 v[88:91], v[202:205], v[160:163], v[88:91]
	v_mfma_f32_16x16x32_bf16 v[38:41], v[202:205], v[164:167], v[40:43]
	v_mfma_f32_16x16x32_bf16 v[92:95], v[206:209], v[124:127], v[92:95]
	v_mfma_f32_16x16x32_bf16 v[96:99], v[206:209], v[128:131], v[96:99]
	v_mfma_f32_16x16x32_bf16 v[100:103], v[206:209], v[160:163], v[100:103]
	v_mfma_f32_16x16x32_bf16 v[42:45], v[206:209], v[164:167], v[44:47]
	v_mfma_f32_16x16x32_bf16 v[104:107], v[210:213], v[124:127], v[104:107]
	v_mfma_f32_16x16x32_bf16 v[108:111], v[210:213], v[128:131], v[108:111]
	v_mfma_f32_16x16x32_bf16 v[112:115], v[210:213], v[160:163], v[112:115]
	v_mfma_f32_16x16x32_bf16 v[46:49], v[210:213], v[164:167], v[48:51]
	s_waitcnt vmcnt(0)
	s_waitcnt lgkmcnt(0)
	s_barrier
	v_mfma_f32_16x16x32_bf16 v[136:139], v[18:21], v[124:127], v[136:139]
	v_mfma_f32_16x16x32_bf16 v[140:143], v[18:21], v[128:131], v[140:143]
	v_mfma_f32_16x16x32_bf16 v[144:147], v[18:21], v[160:163], v[144:147]
	v_mfma_f32_16x16x32_bf16 v[16:19], v[18:21], v[164:167], v[52:55]
	v_mfma_f32_16x16x32_bf16 v[50:53], v[22:25], v[124:127], v[64:67]
	v_mfma_f32_16x16x32_bf16 v[64:67], v[22:25], v[128:131], v[116:119]
	v_mfma_f32_16x16x32_bf16 v[116:119], v[22:25], v[160:163], v[148:151]
	v_mfma_f32_16x16x32_bf16 v[20:23], v[22:25], v[164:167], v[56:59]
	v_mfma_f32_16x16x32_bf16 v[54:57], v[26:29], v[124:127], v[120:123]
	v_mfma_f32_16x16x32_bf16 v[120:123], v[26:29], v[128:131], v[152:155]
	v_mfma_f32_16x16x32_bf16 v[148:151], v[26:29], v[160:163], v[156:159]
	v_mfma_f32_16x16x32_bf16 v[24:27], v[26:29], v[164:167], v[60:63]
	v_mfma_f32_16x16x32_bf16 v[0:3], v[30:33], v[124:127], v[0:3]
	s_nop 1
	ds_read_b128 v[58:61], v134
	ds_read_b128 v[124:127], v197
	ds_read_b128 v[152:155], v230
	ds_read_b128 v[156:159], v231
	v_mfma_f32_16x16x32_bf16 v[4:7], v[30:33], v[128:131], v[4:7]
	ds_read_b128 v[128:131], v232
	ds_read_b128 v[168:171], v232 offset:2048
	ds_read_b128 v[172:175], v232 offset:4096
	ds_read_b128 v[176:179], v232 offset:6144
	v_mfma_f32_16x16x32_bf16 v[8:11], v[30:33], v[160:163], v[8:11]
	ds_read_b128 v[160:163], v232 offset:8192
	ds_read_b128 v[180:183], v232 offset:10240
	ds_read_b128 v[198:201], v232 offset:12288
	ds_read_b128 v[202:205], v232 offset:14336
	v_mfma_f32_16x16x32_bf16 v[12:15], v[30:33], v[164:167], v[12:15]
	s_waitcnt lgkmcnt(0)
	v_mfma_f32_16x16x32_bf16 v[28:31], v[128:131], v[58:61], v[68:71]
	v_mfma_f32_16x16x32_bf16 v[68:71], v[128:131], v[124:127], v[72:75]
	v_mfma_f32_16x16x32_bf16 v[72:75], v[128:131], v[152:155], v[76:79]
	v_mfma_f32_16x16x32_bf16 v[32:35], v[128:131], v[156:159], v[34:37]
	v_mfma_f32_16x16x32_bf16 v[76:79], v[168:171], v[58:61], v[80:83]
	v_mfma_f32_16x16x32_bf16 v[80:83], v[168:171], v[124:127], v[84:87]
	v_mfma_f32_16x16x32_bf16 v[84:87], v[168:171], v[152:155], v[88:91]
	v_mfma_f32_16x16x32_bf16 v[36:39], v[168:171], v[156:159], v[38:41]
	v_mfma_f32_16x16x32_bf16 v[96:99], v[172:175], v[124:127], v[96:99]
	v_mfma_f32_16x16x32_bf16 v[100:103], v[172:175], v[152:155], v[100:103]
	v_mfma_f32_16x16x32_bf16 v[40:43], v[172:175], v[156:159], v[42:45]
	v_mfma_f32_16x16x32_bf16 v[104:107], v[176:179], v[58:61], v[104:107]
	v_mfma_f32_16x16x32_bf16 v[108:111], v[176:179], v[124:127], v[108:111]
	v_mfma_f32_16x16x32_bf16 v[128:131], v[172:175], v[58:61], v[92:95]
	v_mfma_f32_16x16x32_bf16 v[164:167], v[176:179], v[152:155], v[112:115]
	v_mfma_f32_16x16x32_bf16 v[168:171], v[176:179], v[156:159], v[46:49]
	ds_read_b128 v[172:175], v233
	ds_read_b128 v[176:179], v234
	ds_read_b128 v[206:209], v235
	ds_read_b128 v[210:213], v236
	ds_read_b128 v[44:47], v238
	ds_read_b128 v[112:115], v238 offset:2048
	ds_read_b128 v[214:217], v238 offset:4096
	ds_read_b128 v[218:221], v238 offset:6144
	v_mfma_f32_16x16x32_bf16 v[136:139], v[160:163], v[58:61], v[136:139]
	v_mfma_f32_16x16x32_bf16 v[140:143], v[160:163], v[124:127], v[140:143]
	v_mfma_f32_16x16x32_bf16 v[48:51], v[180:183], v[58:61], v[50:53]
	v_mfma_f32_16x16x32_bf16 v[64:67], v[180:183], v[124:127], v[64:67]
	v_mfma_f32_16x16x32_bf16 v[20:23], v[180:183], v[156:159], v[20:23]
	v_mfma_f32_16x16x32_bf16 v[144:147], v[160:163], v[152:155], v[144:147]
	v_mfma_f32_16x16x32_bf16 v[160:163], v[160:163], v[156:159], v[16:19]
	v_mfma_f32_16x16x32_bf16 v[222:225], v[180:183], v[152:155], v[116:119]
	v_mfma_f32_16x16x32_bf16 v[180:183], v[198:201], v[58:61], v[54:57]
	v_mfma_f32_16x16x32_bf16 v[226:229], v[198:201], v[124:127], v[120:123]
	v_mfma_f32_16x16x32_bf16 v[148:151], v[198:201], v[152:155], v[148:151]
	v_mfma_f32_16x16x32_bf16 v[198:201], v[198:201], v[156:159], v[24:27]
	v_mfma_f32_16x16x32_bf16 v[230:233], v[202:205], v[58:61], v[0:3]
	v_mfma_f32_16x16x32_bf16 v[234:237], v[202:205], v[124:127], v[4:7]
	v_mfma_f32_16x16x32_bf16 v[152:155], v[202:205], v[152:155], v[8:11]
	v_mfma_f32_16x16x32_bf16 v[202:205], v[202:205], v[156:159], v[12:15]
	ds_read_b128 v[0:3], v238 offset:8192
	ds_read_b128 v[4:7], v238 offset:10240
	ds_read_b128 v[156:159], v238 offset:12288
	ds_read_b128 v[238:241], v238 offset:14336
	s_waitcnt lgkmcnt(0)
	v_mfma_f32_16x16x32_bf16 v[124:127], v[44:47], v[172:175], v[28:31]
	v_mfma_f32_16x16x32_bf16 v[92:95], v[44:47], v[176:179], v[68:71]
	v_mfma_f32_16x16x32_bf16 v[60:63], v[44:47], v[206:209], v[72:75]
	v_mfma_f32_16x16x32_bf16 v[28:31], v[44:47], v[210:213], v[32:35]
	v_mfma_f32_16x16x32_bf16 v[120:123], v[112:115], v[172:175], v[76:79]
	v_mfma_f32_16x16x32_bf16 v[88:91], v[112:115], v[176:179], v[80:83]
	v_mfma_f32_16x16x32_bf16 v[56:59], v[112:115], v[206:209], v[84:87]
	v_mfma_f32_16x16x32_bf16 v[24:27], v[112:115], v[210:213], v[36:39]
	v_mfma_f32_16x16x32_bf16 v[116:119], v[214:217], v[172:175], v[128:131]
	v_mfma_f32_16x16x32_bf16 v[84:87], v[214:217], v[176:179], v[96:99]
	v_mfma_f32_16x16x32_bf16 v[52:55], v[214:217], v[206:209], v[100:103]
	v_mfma_f32_16x16x32_bf16 v[16:19], v[214:217], v[210:213], v[40:43]
	v_mfma_f32_16x16x32_bf16 v[112:115], v[218:221], v[172:175], v[104:107]
	v_mfma_f32_16x16x32_bf16 v[80:83], v[218:221], v[176:179], v[108:111]
	v_mfma_f32_16x16x32_bf16 v[44:47], v[218:221], v[206:209], v[164:167]
	v_mfma_f32_16x16x32_bf16 v[12:15], v[218:221], v[210:213], v[168:171]
	v_mfma_f32_16x16x32_bf16 v[108:111], v[0:3], v[172:175], v[136:139]
	s_waitcnt vmcnt(0)
	s_waitcnt lgkmcnt(0)
	s_barrier
	v_mfma_f32_16x16x32_bf16 v[72:75], v[0:3], v[176:179], v[140:143]
	s_nop 0
	v_mov_b32_e32 v139, v184
	s_andn2_b64 vcc, exec, s[16:17]
	v_ashrrev_i32_e32 v136, 8, v139
	v_bfe_u32 v137, v139, 4, 2
	v_mfma_f32_16x16x32_bf16 v[40:43], v[0:3], v[206:209], v[144:147]
	v_lshlrev_b32_e32 v138, 2, v137
	v_lshlrev_b32_e32 v140, 7, v136
	v_mfma_f32_16x16x32_bf16 v[8:11], v[0:3], v[210:213], v[160:163]
	v_mfma_f32_16x16x32_bf16 v[0:3], v[4:7], v[210:213], v[20:23]
	s_nop 2
	v_cndmask_b32_e64 v20, 0, 1, s[16:17]
	v_cmp_ne_u32_e64 s[2:3], 1, v20
	v_add_u32_e32 v20, v140, v138
	v_mfma_f32_16x16x32_bf16 v[100:103], v[4:7], v[172:175], v[48:51]
	v_mfma_f32_16x16x32_bf16 v[68:71], v[4:7], v[176:179], v[64:67]
	v_mfma_f32_16x16x32_bf16 v[36:39], v[4:7], v[206:209], v[222:225]
	v_mfma_f32_16x16x32_bf16 v[96:99], v[156:159], v[172:175], v[180:183]
	v_mfma_f32_16x16x32_bf16 v[64:67], v[156:159], v[176:179], v[226:229]
	v_mfma_f32_16x16x32_bf16 v[32:35], v[156:159], v[206:209], v[148:151]
	v_mfma_f32_16x16x32_bf16 v[4:7], v[156:159], v[210:213], v[198:201]
	v_subrev_u32_e32 v156, s4, v20
	v_mfma_f32_16x16x32_bf16 v[104:107], v[238:241], v[172:175], v[230:233]
	v_mfma_f32_16x16x32_bf16 v[76:79], v[238:241], v[176:179], v[234:237]
	v_mfma_f32_16x16x32_bf16 v[48:51], v[238:241], v[206:209], v[152:155]
	v_mfma_f32_16x16x32_bf16 v[20:23], v[238:241], v[210:213], v[202:205]
	s_cbranch_vccnz .LBB0_2120
	v_add_u32_e32 v128, s31, v156
	v_ashrrev_i32_e32 v129, 31, v128
	v_lshlrev_b64 v[142:143], 2, v[128:129]
	v_lshl_add_u64 v[128:129], s[8:9], 0, v[142:143]
	v_lshl_add_u64 v[142:143], s[10:11], 0, v[142:143]
	global_load_dwordx4 v[198:201], v[128:129], off
	global_load_dwordx4 v[202:205], v[128:129], off offset:64
	global_load_dwordx4 v[206:209], v[128:129], off offset:128
	global_load_dwordx4 v[210:213], v[128:129], off offset:192
	global_load_dwordx4 v[214:217], v[128:129], off offset:256
	global_load_dwordx4 v[218:221], v[128:129], off offset:320
	global_load_dwordx4 v[222:225], v[128:129], off offset:384
	global_load_dwordx4 v[226:229], v[128:129], off offset:448
	global_load_dwordx4 v[230:233], v[142:143], off
	global_load_dwordx4 v[234:237], v[142:143], off offset:64
	global_load_dwordx4 v[238:241], v[142:143], off offset:128
	global_load_dwordx4 v[242:245], v[142:143], off offset:192
	global_load_dwordx4 v[246:249], v[142:143], off offset:256
	global_load_dwordx4 v[250:253], v[142:143], off offset:320
	global_load_dwordx4 v[164:167], v[142:143], off offset:384
	global_load_dwordx4 v[168:171], v[142:143], off offset:448
	s_waitcnt vmcnt(0)
	v_pk_add_f32 v[126:127], v[126:127], v[200:201]
	v_pk_add_f32 v[124:125], v[124:125], v[198:199]
	v_pk_mul_f32 v[126:127], v[126:127], v[232:233]
	v_pk_mul_f32 v[124:125], v[124:125], v[230:231]
.LBB0_2120:
	s_and_b64 vcc, exec, s[2:3]
	s_cbranch_vccnz .LBB0_2122
	v_add_u32_e32 v128, s31, v156
	v_ashrrev_i32_e32 v129, 31, v128
	v_lshlrev_b64 v[142:143], 2, v[128:129]
	v_lshl_add_u64 v[128:129], s[8:9], 0, v[142:143]
	v_pk_add_f32 v[122:123], v[122:123], v[204:205]
	v_pk_add_f32 v[120:121], v[120:121], v[202:203]
	v_pk_mul_f32 v[122:123], v[122:123], v[236:237]
	v_pk_mul_f32 v[120:121], v[120:121], v[234:235]
.LBB0_2122:
	v_and_b32_e32 v128, 16, v139
	v_cvt_pk_bf16_f32 v134, v124, v125
	v_cvt_pk_bf16_f32 v141, v126, v127
	v_cvt_pk_bf16_f32 v142, v120, v121
	v_cvt_pk_bf16_f32 v143, v122, v123
	v_cmp_eq_u32_e32 vcc, 0, v128
	v_cmp_ne_u32_e64 s[4:5], 0, v128
	v_mov_b32_e32 v130, v142
	v_mov_b32_e32 v128, v134
	v_mov_b32_e32 v131, v143
	v_mov_b32_e32 v129, v141
	v_permlane16_swap_b32_e32 v128, v130
	s_nop 0
	v_permlane16_swap_b32_e32 v129, v131
	s_and_saveexec_b64 s[6:7], s[4:5]
	s_xor_b64 s[6:7], exec, s[6:7]
	v_mov_b32_e32 v131, v143
	v_mov_b32_e32 v130, v142
	s_andn2_saveexec_b64 s[6:7], s[6:7]
	v_mov_b32_e32 v128, v134
	v_mov_b32_e32 v129, v141
	s_or_b64 exec, exec, s[6:7]
	v_and_b32_e32 v139, 0xcf, v139
	v_lshl_or_b32 v144, s18, 8, v139
	v_add_u32_e32 v134, 12, v138
	v_ashrrev_i32_e32 v145, 31, v144
	v_cndmask_b32_e32 v134, v134, v138, vcc
	v_lshlrev_b64 v[146:147], 11, v[144:145]
	v_or_b32_e32 v142, v134, v140
	v_lshl_add_u64 v[146:147], s[14:15], 0, v[146:147]
	v_lshl_add_u64 v[148:149], s[20:21], 1, v[146:147]
	v_ashrrev_i32_e32 v143, 31, v142
	v_lshl_add_u64 v[146:147], v[142:143], 1, v[148:149]
	s_and_b64 vcc, exec, s[2:3]
	v_ashrrev_i32_e32 v141, 31, v140
	global_store_dwordx4 v[146:147], v[128:131], off nt
	s_cbranch_vccnz .LBB0_2128
	v_mov_b32_e32 v139, v135
	v_lshl_add_u64 v[128:129], v[140:141], 0, v[138:139]
	v_lshl_add_u64 v[128:129], v[128:129], 0, s[20:21]
	v_lshlrev_b64 v[146:147], 2, v[128:129]
	v_lshl_add_u64 v[128:129], s[8:9], 0, v[146:147]
	v_pk_add_f32 v[118:119], v[118:119], v[208:209]
	v_pk_add_f32 v[116:117], v[116:117], v[206:207]
	v_pk_mul_f32 v[118:119], v[118:119], v[240:241]
	v_pk_mul_f32 v[116:117], v[116:117], v[238:239]
.LBB0_2128:
	v_or3_b32 v146, v140, v138, 32
	s_and_b64 vcc, exec, s[2:3]
	v_ashrrev_i32_e32 v147, 31, v146
	s_cbranch_vccnz .LBB0_2130
	v_lshl_add_u64 v[128:129], s[20:21], 0, v[146:147]
	v_lshlrev_b64 v[150:151], 2, v[128:129]
	v_lshl_add_u64 v[128:129], s[8:9], 0, v[150:151]
	v_pk_add_f32 v[114:115], v[114:115], v[212:213]
	v_pk_add_f32 v[112:113], v[112:113], v[210:211]
	v_pk_mul_f32 v[114:115], v[114:115], v[244:245]
	v_pk_mul_f32 v[112:113], v[112:113], v[242:243]
.LBB0_2130:
	v_cvt_pk_bf16_f32 v139, v116, v117
	v_cvt_pk_bf16_f32 v150, v118, v119
	v_cvt_pk_bf16_f32 v151, v112, v113
	v_cvt_pk_bf16_f32 v152, v114, v115
	v_mov_b32_e32 v130, v151
	v_mov_b32_e32 v128, v139
	v_mov_b32_e32 v129, v150
	v_mov_b32_e32 v131, v152
	v_permlane16_swap_b32_e32 v128, v130
	s_nop 0
	v_permlane16_swap_b32_e32 v129, v131
	s_and_saveexec_b64 s[6:7], s[4:5]
	s_xor_b64 s[6:7], exec, s[6:7]
	v_mov_b32_e32 v131, v152
	v_mov_b32_e32 v130, v151
	s_andn2_saveexec_b64 s[6:7], s[6:7]
	v_mov_b32_e32 v128, v139
	v_mov_b32_e32 v129, v150
	s_or_b64 exec, exec, s[6:7]
	v_lshl_add_u64 v[152:153], v[134:135], 0, v[140:141]
	v_lshl_add_u64 v[154:155], v[152:153], 1, v[148:149]
	s_and_b64 vcc, exec, s[2:3]
	global_store_dwordx4 v[154:155], v[128:131], off offset:64 nt
	s_cbranch_vccnz .LBB0_2136
	v_mov_b32_e32 v139, v135
	v_lshl_add_u64 v[128:129], v[140:141], 0, v[138:139]
	v_lshl_add_u64 v[128:129], v[128:129], 0, s[20:21]
	v_lshlrev_b64 v[148:149], 2, v[128:129]
	v_lshl_add_u64 v[128:129], s[8:9], 0, v[148:149]
	v_pk_add_f32 v[110:111], v[110:111], v[216:217]
	v_pk_add_f32 v[108:109], v[108:109], v[214:215]
	v_pk_mul_f32 v[110:111], v[110:111], v[248:249]
	v_pk_mul_f32 v[108:109], v[108:109], v[246:247]
.LBB0_2136:
	v_or3_b32 v148, v140, v138, 64
	s_and_b64 vcc, exec, s[2:3]
	v_ashrrev_i32_e32 v149, 31, v148
	s_cbranch_vccnz .LBB0_2138
	v_lshl_add_u64 v[128:129], s[20:21], 0, v[148:149]
	v_lshlrev_b64 v[150:151], 2, v[128:129]
	v_lshl_add_u64 v[128:129], s[8:9], 0, v[150:151]
	v_pk_add_f32 v[102:103], v[102:103], v[220:221]
	v_pk_add_f32 v[100:101], v[100:101], v[218:219]
	v_pk_mul_f32 v[102:103], v[102:103], v[252:253]
	v_pk_mul_f32 v[100:101], v[100:101], v[250:251]

.LBB0_2141:
	v_mov_b32_e32 v139, v135
	v_lshl_add_u64 v[128:129], v[140:141], 0, v[138:139]
	v_lshl_add_u64 v[128:129], v[128:129], 0, s[20:21]
	v_lshlrev_b64 v[150:151], 2, v[128:129]
	v_lshl_add_u64 v[128:129], s[8:9], 0, v[150:151]
	v_pk_add_f32 v[98:99], v[98:99], v[224:225]
	v_pk_add_f32 v[96:97], v[96:97], v[222:223]
	v_pk_mul_f32 v[98:99], v[98:99], v[166:167]
	v_pk_mul_f32 v[96:97], v[96:97], v[164:165]
.LBB0_2142:
	s_movk_i32 s6, 0x60
	v_or3_b32 v150, v140, v138, s6
	s_and_b64 vcc, exec, s[2:3]
	v_ashrrev_i32_e32 v151, 31, v150
	s_cbranch_vccnz .LBB0_2144
	v_lshl_add_u64 v[128:129], s[20:21], 0, v[150:151]
	v_lshlrev_b64 v[158:159], 2, v[128:129]
	v_lshl_add_u64 v[128:129], s[8:9], 0, v[158:159]
	v_pk_add_f32 v[106:107], v[106:107], v[228:229]
	v_pk_add_f32 v[104:105], v[104:105], v[226:227]
	v_pk_mul_f32 v[106:107], v[106:107], v[170:171]
	v_pk_mul_f32 v[104:105], v[104:105], v[168:169]

.LBB0_2150:
	s_or_b64 exec, exec, s[22:23]
	s_and_b64 vcc, exec, s[2:3]
	s_cbranch_vccnz .LBB0_2152
	v_add_u32_e32 v96, s31, v156
	v_ashrrev_i32_e32 v97, 31, v96
	v_lshlrev_b64 v[100:101], 2, v[96:97]
	v_lshl_add_u64 v[96:97], s[8:9], 0, v[100:101]
	v_pk_add_f32 v[94:95], v[94:95], v[200:201]
	v_pk_add_f32 v[92:93], v[92:93], v[198:199]
	v_pk_mul_f32 v[94:95], v[94:95], v[232:233]
	v_pk_mul_f32 v[92:93], v[92:93], v[230:231]
.LBB0_2152:
	s_and_b64 vcc, exec, s[2:3]
	s_cbranch_vccnz .LBB0_2154
	v_add_u32_e32 v96, s31, v156
	v_ashrrev_i32_e32 v97, 31, v96
	v_lshlrev_b64 v[100:101], 2, v[96:97]
	v_lshl_add_u64 v[96:97], s[8:9], 0, v[100:101]
	v_pk_add_f32 v[90:91], v[90:91], v[204:205]
	v_pk_add_f32 v[88:89], v[88:89], v[202:203]
	v_pk_mul_f32 v[90:91], v[90:91], v[236:237]
	v_pk_mul_f32 v[88:89], v[88:89], v[234:235]
.LBB0_2154:
	v_cvt_pk_bf16_f32 v100, v92, v93
	v_cvt_pk_bf16_f32 v101, v94, v95
	v_cvt_pk_bf16_f32 v102, v88, v89
	v_cvt_pk_bf16_f32 v103, v90, v91
	v_mov_b32_e32 v96, v100
	v_mov_b32_e32 v98, v102
	v_mov_b32_e32 v99, v103
	v_mov_b32_e32 v97, v101
	v_permlane16_swap_b32_e32 v96, v98
	s_nop 0
	v_permlane16_swap_b32_e32 v97, v99
	s_and_saveexec_b64 s[22:23], s[4:5]
	s_xor_b64 s[22:23], exec, s[22:23]
	v_mov_b32_e32 v99, v103
	v_mov_b32_e32 v98, v102
	s_andn2_saveexec_b64 s[22:23], s[22:23]
	v_mov_b32_e32 v96, v100
	v_mov_b32_e32 v97, v101
	s_or_b64 exec, exec, s[22:23]
	v_or_b32_e32 v100, 16, v144
	v_ashrrev_i32_e32 v101, 31, v100
	v_lshlrev_b64 v[102:103], 11, v[100:101]
	v_lshl_add_u64 v[102:103], s[14:15], 0, v[102:103]
	v_lshl_add_u64 v[102:103], s[20:21], 1, v[102:103]
	v_lshl_add_u64 v[104:105], v[142:143], 1, v[102:103]
	s_and_b64 vcc, exec, s[2:3]
	global_store_dwordx4 v[104:105], v[96:99], off nt
	s_cbranch_vccnz .LBB0_2160
	v_mov_b32_e32 v139, v135
	v_lshl_add_u64 v[96:97], v[140:141], 0, v[138:139]
	v_lshl_add_u64 v[96:97], v[96:97], 0, s[20:21]
	v_lshlrev_b64 v[104:105], 2, v[96:97]
	v_lshl_add_u64 v[96:97], s[8:9], 0, v[104:105]
	v_pk_add_f32 v[86:87], v[86:87], v[208:209]
	v_pk_add_f32 v[84:85], v[84:85], v[206:207]
	v_pk_mul_f32 v[86:87], v[86:87], v[240:241]
	v_pk_mul_f32 v[84:85], v[84:85], v[238:239]
.LBB0_2160:
	s_and_b64 vcc, exec, s[2:3]
	s_cbranch_vccnz .LBB0_2162
	v_lshl_add_u64 v[96:97], s[20:21], 0, v[146:147]
	v_lshlrev_b64 v[104:105], 2, v[96:97]
	v_lshl_add_u64 v[96:97], s[8:9], 0, v[104:105]
	v_pk_add_f32 v[82:83], v[82:83], v[212:213]
	v_pk_add_f32 v[80:81], v[80:81], v[210:211]
	v_pk_mul_f32 v[82:83], v[82:83], v[244:245]
	v_pk_mul_f32 v[80:81], v[80:81], v[242:243]
.LBB0_2162:
	v_cvt_pk_bf16_f32 v104, v84, v85
	v_cvt_pk_bf16_f32 v105, v86, v87
	v_cvt_pk_bf16_f32 v106, v80, v81
	v_cvt_pk_bf16_f32 v107, v82, v83
	v_mov_b32_e32 v98, v106
	v_mov_b32_e32 v96, v104
	v_mov_b32_e32 v97, v105
	v_mov_b32_e32 v99, v107
	v_permlane16_swap_b32_e32 v96, v98
	s_nop 0
	v_permlane16_swap_b32_e32 v97, v99
	s_and_saveexec_b64 s[22:23], s[4:5]
	s_xor_b64 s[22:23], exec, s[22:23]
	v_mov_b32_e32 v99, v107
	v_mov_b32_e32 v98, v106
	s_andn2_saveexec_b64 s[22:23], s[22:23]
	v_mov_b32_e32 v96, v104
	v_mov_b32_e32 v97, v105
	s_or_b64 exec, exec, s[22:23]
	v_lshl_add_u64 v[102:103], v[152:153], 1, v[102:103]
	s_and_b64 vcc, exec, s[2:3]
	global_store_dwordx4 v[102:103], v[96:99], off offset:64 nt
	s_cbranch_vccnz .LBB0_2168
	v_mov_b32_e32 v139, v135
	v_lshl_add_u64 v[96:97], v[140:141], 0, v[138:139]
	v_lshl_add_u64 v[96:97], v[96:97], 0, s[20:21]
	v_lshlrev_b64 v[104:105], 2, v[96:97]
	v_lshl_add_u64 v[96:97], s[8:9], 0, v[104:105]
	v_pk_add_f32 v[74:75], v[74:75], v[216:217]
	v_pk_add_f32 v[72:73], v[72:73], v[214:215]
	v_pk_mul_f32 v[74:75], v[74:75], v[248:249]
	v_pk_mul_f32 v[72:73], v[72:73], v[246:247]
.LBB0_2168:
	s_and_b64 vcc, exec, s[2:3]
	s_cbranch_vccnz .LBB0_2170
	v_lshl_add_u64 v[96:97], s[20:21], 0, v[148:149]
	v_lshlrev_b64 v[104:105], 2, v[96:97]
	v_lshl_add_u64 v[96:97], s[8:9], 0, v[104:105]
	v_pk_add_f32 v[70:71], v[70:71], v[220:221]
	v_pk_add_f32 v[68:69], v[68:69], v[218:219]
	v_pk_mul_f32 v[70:71], v[70:71], v[252:253]
	v_pk_mul_f32 v[68:69], v[68:69], v[250:251]

.LBB0_2173:
	v_mov_b32_e32 v139, v135
	v_lshl_add_u64 v[96:97], v[140:141], 0, v[138:139]
	v_lshl_add_u64 v[96:97], v[96:97], 0, s[20:21]
	v_lshlrev_b64 v[104:105], 2, v[96:97]
	v_lshl_add_u64 v[96:97], s[8:9], 0, v[104:105]
	v_pk_add_f32 v[66:67], v[66:67], v[224:225]
	v_pk_add_f32 v[64:65], v[64:65], v[222:223]
	v_pk_mul_f32 v[66:67], v[66:67], v[166:167]
	v_pk_mul_f32 v[64:65], v[64:65], v[164:165]
.LBB0_2174:
	s_and_b64 vcc, exec, s[2:3]
	s_cbranch_vccnz .LBB0_2176
	v_lshl_add_u64 v[96:97], s[20:21], 0, v[150:151]
	v_lshlrev_b64 v[104:105], 2, v[96:97]
	v_lshl_add_u64 v[96:97], s[8:9], 0, v[104:105]
	v_pk_add_f32 v[78:79], v[78:79], v[228:229]
	v_pk_add_f32 v[76:77], v[76:77], v[226:227]
	v_pk_mul_f32 v[78:79], v[78:79], v[170:171]
	v_pk_mul_f32 v[76:77], v[76:77], v[168:169]

.LBB0_2182:
	s_or_b64 exec, exec, s[22:23]
	s_and_b64 vcc, exec, s[2:3]
	s_cbranch_vccnz .LBB0_2184
	v_add_u32_e32 v64, s31, v156
	v_ashrrev_i32_e32 v65, 31, v64
	v_lshlrev_b64 v[68:69], 2, v[64:65]
	v_lshl_add_u64 v[64:65], s[8:9], 0, v[68:69]
	v_pk_add_f32 v[62:63], v[62:63], v[200:201]
	v_pk_add_f32 v[60:61], v[60:61], v[198:199]
	v_pk_mul_f32 v[62:63], v[62:63], v[232:233]
	v_pk_mul_f32 v[60:61], v[60:61], v[230:231]
.LBB0_2184:
	s_and_b64 vcc, exec, s[2:3]
	s_cbranch_vccnz .LBB0_2186
	v_add_u32_e32 v64, s31, v156
	v_ashrrev_i32_e32 v65, 31, v64
	v_lshlrev_b64 v[68:69], 2, v[64:65]
	v_lshl_add_u64 v[64:65], s[8:9], 0, v[68:69]
	v_pk_add_f32 v[58:59], v[58:59], v[204:205]
	v_pk_add_f32 v[56:57], v[56:57], v[202:203]
	v_pk_mul_f32 v[58:59], v[58:59], v[236:237]
	v_pk_mul_f32 v[56:57], v[56:57], v[234:235]
.LBB0_2186:
	v_cvt_pk_bf16_f32 v68, v60, v61
	v_cvt_pk_bf16_f32 v69, v62, v63
	v_cvt_pk_bf16_f32 v70, v56, v57
	v_cvt_pk_bf16_f32 v71, v58, v59
	v_mov_b32_e32 v66, v70
	v_mov_b32_e32 v64, v68
	v_mov_b32_e32 v65, v69
	v_mov_b32_e32 v67, v71
	v_permlane16_swap_b32_e32 v64, v66
	s_nop 0
	v_permlane16_swap_b32_e32 v65, v67
	s_and_saveexec_b64 s[22:23], s[4:5]
	s_xor_b64 s[22:23], exec, s[22:23]
	v_mov_b32_e32 v67, v71
	v_mov_b32_e32 v66, v70
	s_andn2_saveexec_b64 s[22:23], s[22:23]
	v_mov_b32_e32 v64, v68
	v_mov_b32_e32 v65, v69
	s_or_b64 exec, exec, s[22:23]
	v_or_b32_e32 v68, 32, v144
	v_ashrrev_i32_e32 v69, 31, v68
	v_lshlrev_b64 v[70:71], 11, v[68:69]
	v_lshl_add_u64 v[70:71], s[14:15], 0, v[70:71]
	v_lshl_add_u64 v[70:71], s[20:21], 1, v[70:71]
	v_lshl_add_u64 v[72:73], v[142:143], 1, v[70:71]
	s_and_b64 vcc, exec, s[2:3]
	global_store_dwordx4 v[72:73], v[64:67], off nt
	s_cbranch_vccnz .LBB0_2192
	v_mov_b32_e32 v139, v135
	v_lshl_add_u64 v[64:65], v[140:141], 0, v[138:139]
	v_lshl_add_u64 v[64:65], v[64:65], 0, s[20:21]
	v_lshlrev_b64 v[72:73], 2, v[64:65]
	v_lshl_add_u64 v[64:65], s[8:9], 0, v[72:73]
	v_pk_add_f32 v[54:55], v[54:55], v[208:209]
	v_pk_add_f32 v[52:53], v[52:53], v[206:207]
	v_pk_mul_f32 v[54:55], v[54:55], v[240:241]
	v_pk_mul_f32 v[52:53], v[52:53], v[238:239]
.LBB0_2192:
	s_and_b64 vcc, exec, s[2:3]
	s_cbranch_vccnz .LBB0_2194
	v_lshl_add_u64 v[64:65], s[20:21], 0, v[146:147]
	v_lshlrev_b64 v[72:73], 2, v[64:65]
	v_lshl_add_u64 v[64:65], s[8:9], 0, v[72:73]
	v_pk_add_f32 v[46:47], v[46:47], v[212:213]
	v_pk_add_f32 v[44:45], v[44:45], v[210:211]
	v_pk_mul_f32 v[46:47], v[46:47], v[244:245]
	v_pk_mul_f32 v[44:45], v[44:45], v[242:243]
.LBB0_2194:
	v_cvt_pk_bf16_f32 v72, v52, v53
	v_cvt_pk_bf16_f32 v73, v54, v55
	v_cvt_pk_bf16_f32 v74, v44, v45
	v_cvt_pk_bf16_f32 v75, v46, v47
	v_mov_b32_e32 v64, v72
	v_mov_b32_e32 v66, v74
	v_mov_b32_e32 v67, v75
	v_mov_b32_e32 v65, v73
	v_permlane16_swap_b32_e32 v64, v66
	s_nop 0
	v_permlane16_swap_b32_e32 v65, v67
	s_and_saveexec_b64 s[22:23], s[4:5]
	s_xor_b64 s[22:23], exec, s[22:23]
	v_mov_b32_e32 v67, v75
	v_mov_b32_e32 v66, v74
	s_andn2_saveexec_b64 s[22:23], s[22:23]
	v_mov_b32_e32 v64, v72
	v_mov_b32_e32 v65, v73
	s_or_b64 exec, exec, s[22:23]
	v_lshl_add_u64 v[70:71], v[152:153], 1, v[70:71]
	s_and_b64 vcc, exec, s[2:3]
	global_store_dwordx4 v[70:71], v[64:67], off offset:64 nt
	s_cbranch_vccnz .LBB0_2200
	v_mov_b32_e32 v139, v135
	v_lshl_add_u64 v[64:65], v[140:141], 0, v[138:139]
	v_lshl_add_u64 v[64:65], v[64:65], 0, s[20:21]
	v_lshlrev_b64 v[72:73], 2, v[64:65]
	v_lshl_add_u64 v[64:65], s[8:9], 0, v[72:73]
	v_pk_add_f32 v[42:43], v[42:43], v[216:217]
	v_pk_add_f32 v[40:41], v[40:41], v[214:215]
	v_pk_mul_f32 v[42:43], v[42:43], v[248:249]
	v_pk_mul_f32 v[40:41], v[40:41], v[246:247]
.LBB0_2200:
	s_and_b64 vcc, exec, s[2:3]
	s_cbranch_vccnz .LBB0_2202
	v_lshl_add_u64 v[64:65], s[20:21], 0, v[148:149]
	v_lshlrev_b64 v[72:73], 2, v[64:65]
	v_lshl_add_u64 v[64:65], s[8:9], 0, v[72:73]
	v_pk_add_f32 v[38:39], v[38:39], v[220:221]
	v_pk_add_f32 v[36:37], v[36:37], v[218:219]
	v_pk_mul_f32 v[38:39], v[38:39], v[252:253]
	v_pk_mul_f32 v[36:37], v[36:37], v[250:251]

.LBB0_2205:
	v_mov_b32_e32 v139, v135
	v_lshl_add_u64 v[64:65], v[140:141], 0, v[138:139]
	v_lshl_add_u64 v[64:65], v[64:65], 0, s[20:21]
	v_lshlrev_b64 v[72:73], 2, v[64:65]
	v_lshl_add_u64 v[64:65], s[8:9], 0, v[72:73]
	v_pk_add_f32 v[34:35], v[34:35], v[224:225]
	v_pk_add_f32 v[32:33], v[32:33], v[222:223]
	v_pk_mul_f32 v[34:35], v[34:35], v[166:167]
	v_pk_mul_f32 v[32:33], v[32:33], v[164:165]
.LBB0_2206:
	s_and_b64 vcc, exec, s[2:3]
	s_cbranch_vccnz .LBB0_2208
	v_lshl_add_u64 v[64:65], s[20:21], 0, v[150:151]
	v_lshlrev_b64 v[72:73], 2, v[64:65]
	v_lshl_add_u64 v[64:65], s[8:9], 0, v[72:73]
	v_pk_add_f32 v[50:51], v[50:51], v[228:229]
	v_pk_add_f32 v[48:49], v[48:49], v[226:227]
	v_pk_mul_f32 v[50:51], v[50:51], v[170:171]
	v_pk_mul_f32 v[48:49], v[48:49], v[168:169]

.LBB0_2214:
	s_or_b64 exec, exec, s[22:23]
	s_and_b64 vcc, exec, s[2:3]
	s_cbranch_vccnz .LBB0_2216
	v_add_u32_e32 v32, s31, v156
	v_ashrrev_i32_e32 v33, 31, v32
	v_lshlrev_b64 v[36:37], 2, v[32:33]
	v_lshl_add_u64 v[32:33], s[8:9], 0, v[36:37]
	v_pk_add_f32 v[30:31], v[30:31], v[200:201]
	v_pk_add_f32 v[28:29], v[28:29], v[198:199]
	v_pk_mul_f32 v[30:31], v[30:31], v[232:233]
	v_pk_mul_f32 v[28:29], v[28:29], v[230:231]
.LBB0_2216:
	s_and_b64 vcc, exec, s[2:3]
	s_cbranch_vccnz .LBB0_2218
	v_add_u32_e32 v32, s31, v156
	v_ashrrev_i32_e32 v33, 31, v32
	v_lshlrev_b64 v[36:37], 2, v[32:33]
	v_lshl_add_u64 v[32:33], s[8:9], 0, v[36:37]
	v_pk_add_f32 v[26:27], v[26:27], v[204:205]
	v_pk_add_f32 v[24:25], v[24:25], v[202:203]
	v_pk_mul_f32 v[26:27], v[26:27], v[236:237]
	v_pk_mul_f32 v[24:25], v[24:25], v[234:235]
.LBB0_2218:
	v_cvt_pk_bf16_f32 v36, v28, v29
	v_cvt_pk_bf16_f32 v37, v30, v31
	v_cvt_pk_bf16_f32 v38, v24, v25
	v_cvt_pk_bf16_f32 v39, v26, v27
	v_mov_b32_e32 v32, v36
	v_mov_b32_e32 v34, v38
	v_mov_b32_e32 v35, v39
	v_mov_b32_e32 v33, v37
	v_permlane16_swap_b32_e32 v32, v34
	s_nop 0
	v_permlane16_swap_b32_e32 v33, v35
	s_and_saveexec_b64 s[22:23], s[4:5]
	s_xor_b64 s[22:23], exec, s[22:23]
	v_mov_b32_e32 v35, v39
	v_mov_b32_e32 v34, v38
	s_andn2_saveexec_b64 s[22:23], s[22:23]
	v_mov_b32_e32 v32, v36
	v_mov_b32_e32 v33, v37
	s_or_b64 exec, exec, s[22:23]
	v_or_b32_e32 v36, 48, v144
	v_ashrrev_i32_e32 v37, 31, v36
	v_lshlrev_b64 v[38:39], 11, v[36:37]
	v_lshl_add_u64 v[38:39], s[14:15], 0, v[38:39]
	v_lshl_add_u64 v[38:39], s[20:21], 1, v[38:39]
	v_lshl_add_u64 v[40:41], v[142:143], 1, v[38:39]
	s_and_b64 vcc, exec, s[2:3]
	global_store_dwordx4 v[40:41], v[32:35], off nt
	s_cbranch_vccnz .LBB0_2224
	v_mov_b32_e32 v139, v135
	v_lshl_add_u64 v[32:33], v[140:141], 0, v[138:139]
	v_lshl_add_u64 v[32:33], v[32:33], 0, s[20:21]
	v_lshlrev_b64 v[40:41], 2, v[32:33]
	v_lshl_add_u64 v[32:33], s[8:9], 0, v[40:41]
	v_pk_add_f32 v[18:19], v[18:19], v[208:209]
	v_pk_add_f32 v[16:17], v[16:17], v[206:207]
	v_pk_mul_f32 v[18:19], v[18:19], v[240:241]
	v_pk_mul_f32 v[16:17], v[16:17], v[238:239]
.LBB0_2224:
	s_and_b64 vcc, exec, s[2:3]
	s_cbranch_vccnz .LBB0_2226
	v_lshl_add_u64 v[32:33], s[20:21], 0, v[146:147]
	v_lshlrev_b64 v[40:41], 2, v[32:33]
	v_lshl_add_u64 v[32:33], s[8:9], 0, v[40:41]
	v_pk_add_f32 v[14:15], v[14:15], v[212:213]
	v_pk_add_f32 v[12:13], v[12:13], v[210:211]
	v_pk_mul_f32 v[14:15], v[14:15], v[244:245]
	v_pk_mul_f32 v[12:13], v[12:13], v[242:243]
.LBB0_2226:
	v_cvt_pk_bf16_f32 v40, v16, v17
	v_cvt_pk_bf16_f32 v41, v18, v19
	v_cvt_pk_bf16_f32 v42, v12, v13
	v_cvt_pk_bf16_f32 v43, v14, v15
	v_mov_b32_e32 v34, v42
	v_mov_b32_e32 v32, v40
	v_mov_b32_e32 v33, v41
	v_mov_b32_e32 v35, v43
	v_permlane16_swap_b32_e32 v32, v34
	s_nop 0
	v_permlane16_swap_b32_e32 v33, v35
	s_and_saveexec_b64 s[22:23], s[4:5]
	s_xor_b64 s[22:23], exec, s[22:23]
	v_mov_b32_e32 v35, v43
	v_mov_b32_e32 v34, v42
	s_andn2_saveexec_b64 s[22:23], s[22:23]
	v_mov_b32_e32 v32, v40
	v_mov_b32_e32 v33, v41
	s_or_b64 exec, exec, s[22:23]
	v_lshl_add_u64 v[38:39], v[152:153], 1, v[38:39]
	s_and_b64 vcc, exec, s[2:3]
	global_store_dwordx4 v[38:39], v[32:35], off offset:64 nt
	s_cbranch_vccnz .LBB0_2232
	v_mov_b32_e32 v139, v135
	v_lshl_add_u64 v[32:33], v[140:141], 0, v[138:139]
	v_lshl_add_u64 v[32:33], v[32:33], 0, s[20:21]
	v_lshlrev_b64 v[40:41], 2, v[32:33]
	v_lshl_add_u64 v[32:33], s[8:9], 0, v[40:41]
	v_pk_add_f32 v[10:11], v[10:11], v[216:217]
	v_pk_add_f32 v[8:9], v[8:9], v[214:215]
	v_pk_mul_f32 v[10:11], v[10:11], v[248:249]
	v_pk_mul_f32 v[8:9], v[8:9], v[246:247]
.LBB0_2232:
	s_and_b64 vcc, exec, s[2:3]
	s_cbranch_vccnz .LBB0_2234
	v_lshl_add_u64 v[32:33], s[20:21], 0, v[148:149]
	v_lshlrev_b64 v[40:41], 2, v[32:33]
	v_lshl_add_u64 v[32:33], s[8:9], 0, v[40:41]
	v_pk_add_f32 v[2:3], v[2:3], v[220:221]
	v_pk_add_f32 v[0:1], v[0:1], v[218:219]
	v_pk_mul_f32 v[2:3], v[2:3], v[252:253]
	v_pk_mul_f32 v[0:1], v[0:1], v[250:251]

.LBB0_2237:
	v_mov_b32_e32 v139, v135
	v_lshl_add_u64 v[32:33], v[140:141], 0, v[138:139]
	v_lshl_add_u64 v[32:33], v[32:33], 0, s[20:21]
	v_lshlrev_b64 v[40:41], 2, v[32:33]
	v_lshl_add_u64 v[32:33], s[8:9], 0, v[40:41]
	v_pk_add_f32 v[6:7], v[6:7], v[224:225]
	v_pk_add_f32 v[4:5], v[4:5], v[222:223]
	v_pk_mul_f32 v[6:7], v[6:7], v[166:167]
	v_pk_mul_f32 v[4:5], v[4:5], v[164:165]
.LBB0_2238:
	s_and_b64 vcc, exec, s[2:3]
	s_cbranch_vccnz .LBB0_2240
	v_lshl_add_u64 v[32:33], s[20:21], 0, v[150:151]
	v_lshlrev_b64 v[40:41], 2, v[32:33]
	v_lshl_add_u64 v[32:33], s[8:9], 0, v[40:41]
	v_pk_add_f32 v[22:23], v[22:23], v[228:229]
	v_pk_add_f32 v[20:21], v[20:21], v[226:227]
	v_pk_mul_f32 v[22:23], v[22:23], v[170:171]
	v_pk_mul_f32 v[20:21], v[20:21], v[168:169]
